# E1 + XCD-local grid barriers (mixout->FFN-in, FFN-in3->FFN-out3, FFN-out3->final norm with XCD-aligned rows)
# speedup vs baseline: 1.0225x; 1.0104x over previous
.LBB0_14:
	v_cmp_gt_u32_e32 vcc, 5, v204
	s_and_saveexec_b64 s[2:3], vcc
	v_lshl_add_u32 v0, v204, 2, 0
	v_add_u32_e32 v0, 0x20800, v0
	v_mov_b32_e32 v1, 0
	ds_write_b32 v0, v1
	s_or_b64 exec, exec, s[2:3]
	s_waitcnt lgkmcnt(0)
	s_add_u32 s40, s0, 0x13760800
	s_addc_u32 s41, s1, 0
	s_sub_i32 s4, s37, s36
	s_cmp_lt_i32 s4, 2
	s_cselect_b64 s[2:3], -1, 0
	s_cmp_gt_i32 s4, 1
	s_cselect_b64 s[8:9], -1, 0
	s_mov_b32 s54, 0
	s_and_b64 vcc, exec, s[2:3]
	v_cmp_eq_u32_e64 s[4:5], 0, v204
	s_barrier
	s_cbranch_vccnz .LBB0_21
	s_getreg_b32 s6, hwreg(HW_REG_XCC_ID, 0, 4)
	s_and_b32 s54, s6, 15
	s_and_saveexec_b64 s[6:7], s[4:5]
	s_cbranch_execz .LBB0_20
	s_mov_b64 s[4:5], exec
	v_mbcnt_lo_u32_b32 v0, s4, 0
	v_mbcnt_hi_u32_b32 v0, s5, v0
	v_cmp_eq_u32_e32 vcc, 0, v0
	s_and_b64 s[10:11], exec, vcc
	s_mov_b64 exec, s[10:11]
	s_cbranch_execz .LBB0_20
	s_lshl_b32 s10, s54, 8
	s_bcnt1_i32_b64 s4, s[4:5]
	v_mov_b32_e32 v0, s10
	v_mov_b32_e32 v1, s4
	global_atomic_add v0, v1, s[40:41] offset:1024

.LBB0_151:
	s_nor_b64 s[4:5], s[6:7], s[2:3]
	s_and_b32 s2, s38, 7
	s_mov_b64 s[6:7], s[88:89]
	s_cmp_eq_u32 s2, 0
	s_load_dwordx2 s[2:3], s[6:7], 0xb8
	s_cselect_b64 s[8:9], -1, 0
	s_cmp_lt_u32 s54, 8
	s_cselect_b64 s[10:11], -1, 0
	s_and_b64 s[4:5], s[4:5], s[8:9]
	s_and_b64 s[8:9], s[4:5], s[10:11]
	s_and_saveexec_b64 s[4:5], s[8:9]
	s_cbranch_execz .LBB0_161
	v_mov_b32_e32 v0, 0x13763000
	s_waitcnt lgkmcnt(0)
	global_load_dword v1, v0, s[2:3] offset:3600 sc1
	s_lshr_b32 s8, s38, 3
	s_waitcnt vmcnt(0)
	v_cmp_ne_u32_e32 vcc, s8, v1
	s_cbranch_vccnz .LBB0_161
	global_load_dword v0, v0, s[2:3] offset:3856 sc1
	s_waitcnt vmcnt(0)
	v_cmp_ne_u32_e32 vcc, s8, v0
	s_cbranch_vccnz .LBB0_161
	v_mov_b32_e32 v0, 0x13764000
	global_load_dword v1, v0, s[2:3] offset:16 sc1
	s_waitcnt vmcnt(0)
	v_cmp_ne_u32_e32 vcc, s8, v1
	s_cbranch_vccnz .LBB0_161
	global_load_dword v0, v0, s[2:3] offset:272 sc1
	s_waitcnt vmcnt(0)
	v_cmp_ne_u32_e32 vcc, s8, v0
	s_cbranch_vccnz .LBB0_161
	v_mov_b32_e32 v0, 0x13764000
	global_load_dword v1, v0, s[2:3] offset:528 sc1
	s_waitcnt vmcnt(0)
	v_cmp_ne_u32_e32 vcc, s8, v1
	s_cbranch_vccnz .LBB0_161
	global_load_dword v0, v0, s[2:3] offset:784 sc1
	s_waitcnt vmcnt(0)
	v_cmp_ne_u32_e32 vcc, s8, v0
	s_cbranch_vccnz .LBB0_161
	v_mov_b32_e32 v0, 0x13764000
	global_load_dword v1, v0, s[2:3] offset:1040 sc1
	s_waitcnt vmcnt(0)
	v_cmp_ne_u32_e32 vcc, s8, v1
	s_cbranch_vccnz .LBB0_161
	global_load_dword v0, v0, s[2:3] offset:1296 sc1
	s_waitcnt vmcnt(0)
	v_cmp_ne_u32_e32 vcc, s8, v0
	s_cbranch_vccnz .LBB0_161
	s_add_i32 s8, 0, 0x20808
	v_mov_b32_e32 v0, s8
	ds_read_b32 v0, v0
	s_add_i32 s8, 0, 0x2080c
	v_mov_b32_e32 v1, s8
	s_waitcnt lgkmcnt(0)
	v_lshlrev_b32_e32 v0, 3, v0
	v_or_b32_e32 v0, s54, v0
	ds_write_b32 v1, v0
	v_mov_b32_e32 v0, 1
	v_mov_b32_e32 v1, 0x20810
	ds_write_b32 v1, v0

.LBB0_530:
	s_andn2_saveexec_b64 s[2:3], s[42:43]
	s_cbranch_execz .LBB0_548
	s_mov_b64 s[42:43], exec
	v_mov_b32_e32 v1, 0x20810
	ds_read_b32 v1, v1
	s_waitcnt lgkmcnt(0)
	v_readfirstlane_b32 s2, v1
	s_cmp_lg_u32 s2, 0
	s_cbranch_scc1 .Lxl_fin_skip
	buffer_wbl2 sc1
	s_waitcnt lgkmcnt(0)
	s_waitcnt vmcnt(0)
	v_mbcnt_lo_u32_b32 v1, s42, 0
	v_mbcnt_hi_u32_b32 v1, s43, v1
	v_cmp_eq_u32_e32 vcc, 0, v1
	s_and_saveexec_b64 s[44:45], vcc
	s_cbranch_execz .LBB0_533
	s_bcnt1_i32_b64 s2, s[42:43]
	v_mov_b32_e32 v2, s2
	v_readlane_b32 s2, v255, 10
	v_readlane_b32 s3, v255, 11
	s_nop 4
	global_atomic_add v2, v97, v2, s[2:3] sc0

.Lxl_fin_skip:
	v_readlane_b32 s2, v255, 8
	v_readlane_b32 s3, v255, 9
	v_mov_b32_e32 v0, 1
	s_waitcnt vmcnt(0)
	buffer_inv sc1
	s_nop 1
	global_atomic_add v97, v0, s[2:3]
	s_waitcnt vmcnt(0)

.LBB0_961:
	s_andn2_saveexec_b64 s[2:3], s[42:43]
	s_cbranch_execz .LBB0_979
	s_mov_b64 s[42:43], exec
	s_cmp_lg_u32 s36, 7
	s_cbranch_scc1 .Lxl_fout_no
	v_mov_b32_e32 v1, 0x20810
	ds_read_b32 v1, v1
	s_waitcnt lgkmcnt(0)
	v_readfirstlane_b32 s2, v1
	s_cmp_lg_u32 s2, 0
	s_cbranch_scc1 .Lxl_fout_skip
.Lxl_fout_no:
	buffer_wbl2 sc1
	s_waitcnt lgkmcnt(0)
	s_waitcnt vmcnt(0)
	v_mbcnt_lo_u32_b32 v1, s42, 0
	v_mbcnt_hi_u32_b32 v1, s43, v1
	v_cmp_eq_u32_e32 vcc, 0, v1
	s_and_saveexec_b64 s[44:45], vcc
	s_cbranch_execz .LBB0_964
	s_bcnt1_i32_b64 s2, s[42:43]
	v_mov_b32_e32 v2, s2
	v_readlane_b32 s2, v255, 10
	v_readlane_b32 s3, v255, 11
	s_nop 4
	global_atomic_add v2, v97, v2, s[2:3] sc0

.LBB0_1223:
	s_andn2_saveexec_b64 s[2:3], s[2:3]
	s_cbranch_execz .LBB0_1241
	s_mov_b64 s[2:3], exec
	v_mov_b32_e32 v1, 0x20810
	ds_read_b32 v1, v1
	s_waitcnt lgkmcnt(0)
	v_readfirstlane_b32 s4, v1
	s_cmp_lg_u32 s4, 0
	s_cbranch_scc1 .Lxl_final_skip
	buffer_wbl2 sc1
	s_waitcnt lgkmcnt(0)
	s_waitcnt vmcnt(0)
	v_mbcnt_lo_u32_b32 v1, s2, 0
	v_mbcnt_hi_u32_b32 v1, s3, v1
	v_cmp_eq_u32_e32 vcc, 0, v1
	s_and_saveexec_b64 s[4:5], vcc
	s_cbranch_execz .LBB0_1226
	s_bcnt1_i32_b64 s2, s[2:3]
	v_mov_b32_e32 v3, s2
	v_readlane_b32 s2, v255, 10
	v_mov_b32_e32 v2, 0
	v_readlane_b32 s3, v255, 11
	s_nop 4
	global_atomic_add v2, v2, v3, s[2:3] sc0

.Lxl_final_skip:
	v_readlane_b32 s2, v255, 8
	v_mov_b32_e32 v0, 0
	v_mov_b32_e32 v1, 1
	v_readlane_b32 s3, v255, 9
	s_waitcnt vmcnt(0)
	buffer_inv sc1
	s_nop 2
	global_atomic_add v0, v1, s[2:3]
	s_waitcnt vmcnt(0)

.LBB0_1242:
	v_mov_b32_e32 v0, 0x2080c
	ds_read_b32 v0, v0
	s_waitcnt lgkmcnt(0)
	v_readfirstlane_b32 s0, v0
	s_and_b32 s1, s0, 7
	s_lshr_b32 s0, s0, 3
	s_mulk_i32 s1, 0x600
	s_lshl_b32 s0, s0, 3
	s_add_i32 s0, s0, s1
	s_add_i32 s100, s1, 0x5ff
	s_movk_i32 s33, 0x100
	s_mov_b64 s[18:19], 0x200
	s_mov_b64 s[20:21], 0x100000
	s_waitcnt vmcnt(0)
	v_ashrrev_i32_e32 v0, 6, v204
	s_movk_i32 s12, 0x3000
	v_add_u32_e32 v16, s0, v0
	v_cmp_gt_i32_e32 vcc, s12, v16
	s_and_saveexec_b64 s[0:1], vcc
	s_cbranch_execz .LBB0_1245
	s_load_dwordx4 s[4:7], s[88:89], 0xa8
	s_load_dwordx2 s[8:9], s[88:89], 0xb8
	v_lshlrev_b32_e32 v17, 2, v204
	v_and_b32_e32 v18, 0xfc, v17
	v_lshlrev_b32_e32 v22, 2, v18
	s_waitcnt lgkmcnt(0)
	global_load_dwordx4 v[0:3], v22, s[4:5]
	global_load_dwordx4 v[4:7], v22, s[4:5] offset:1024
	global_load_dwordx4 v[8:11], v22, s[4:5] offset:2048
	global_load_dwordx4 v[12:15], v22, s[4:5] offset:3072
	v_and_b32_e32 v26, 60, v17
	v_and_b32_e32 v17, 64, v205
	v_add_u32_e32 v17, 64, v17
	v_xor_b32_e32 v24, 8, v205
	v_cmp_lt_i32_e32 vcc, v24, v17
	v_mov_b32_e32 v23, 0
	v_lshlrev_b32_e32 v18, 1, v18
	v_cndmask_b32_e32 v24, v205, v24, vcc
	v_lshlrev_b32_e32 v32, 2, v24
	v_xor_b32_e32 v24, 4, v205
	v_cmp_lt_i32_e32 vcc, v24, v17
	v_mov_b32_e32 v19, v23
	v_lshl_add_u64 v[18:19], s[8:9], 0, v[18:19]
	v_cndmask_b32_e32 v24, v205, v24, vcc
	v_lshlrev_b32_e32 v33, 2, v24
	v_xor_b32_e32 v24, 2, v205
	v_cmp_lt_i32_e32 vcc, v24, v17
	s_mov_b64 s[0:1], 0x57c8000
	v_lshl_add_u64 v[18:19], v[18:19], 0, s[0:1]
	v_cndmask_b32_e32 v24, v205, v24, vcc
	v_lshlrev_b32_e32 v34, 2, v24
	v_xor_b32_e32 v24, 1, v205
	v_cmp_lt_i32_e32 vcc, v24, v17
	v_mov_b32_e32 v27, v23
	s_mov_b64 s[0:1], 0x13648000
	v_cndmask_b32_e32 v17, v205, v24, vcc
	v_lshlrev_b32_e32 v35, 2, v17
	v_ashrrev_i32_e32 v17, 31, v16
	v_lshlrev_b64 v[28:29], 6, v[16:17]
	v_lshlrev_b64 v[24:25], 12, v[16:17]
	v_and_b32_e32 v30, 63, v204
	v_or_b32_e32 v28, v28, v26
	v_lshl_add_u64 v[20:21], s[8:9], 0, v[26:27]
	v_lshl_or_b32 v24, v30, 4, v24
	v_lshl_add_u64 v[26:27], v[28:29], 0, s[0:1]
	v_lshlrev_b64 v[28:29], 11, v[16:17]
	v_lshl_add_u64 v[20:21], v[20:21], 0, s[0:1]
	v_lshl_add_u64 v[22:23], s[6:7], 0, v[22:23]
	v_lshl_add_u64 v[24:25], s[6:7], 0, v[24:25]
	s_lshl_b64 s[4:5], s[18:19], 12
	s_lshl_b64 s[6:7], s[18:19], 6
	v_lshl_or_b32 v28, v30, 3, v28
	s_mov_b64 s[10:11], 0
	v_mov_b32_e32 v17, 0x358637bd
	s_mov_b32 s13, 0xf800000
	v_mov_b32_e32 v36, 0x260
	s_mov_b32 s14, s100

	.amdhsa_kernel _Z14fwd_megakernel6Params
		.amdhsa_group_segment_fixed_size 0
		.amdhsa_private_segment_fixed_size 0
		.amdhsa_kernarg_size 456
		.amdhsa_user_sgpr_count 2
		.amdhsa_user_sgpr_dispatch_ptr 0
		.amdhsa_user_sgpr_queue_ptr 0
		.amdhsa_user_sgpr_kernarg_segment_ptr 1
		.amdhsa_user_sgpr_dispatch_id 0
		.amdhsa_user_sgpr_kernarg_preload_length 0
		.amdhsa_user_sgpr_kernarg_preload_offset 0
		.amdhsa_user_sgpr_private_segment_size 0
		.amdhsa_uses_dynamic_stack 0
		.amdhsa_enable_private_segment 0
		.amdhsa_system_sgpr_workgroup_id_x 1
		.amdhsa_system_sgpr_workgroup_id_y 0
		.amdhsa_system_sgpr_workgroup_id_z 0
		.amdhsa_system_sgpr_workgroup_info 0
		.amdhsa_system_vgpr_workitem_id 2
		.amdhsa_next_free_vgpr 256
		.amdhsa_next_free_sgpr 102
		.amdhsa_accum_offset 256
		.amdhsa_reserve_vcc 1
		.amdhsa_float_round_mode_32 0
		.amdhsa_float_round_mode_16_64 0
		.amdhsa_float_denorm_mode_32 3
		.amdhsa_float_denorm_mode_16_64 3
		.amdhsa_dx10_clamp 1
		.amdhsa_ieee_mode 1
		.amdhsa_fp16_overflow 0
		.amdhsa_tg_split 0
		.amdhsa_exception_fp_ieee_invalid_op 0
		.amdhsa_exception_fp_denorm_src 0
		.amdhsa_exception_fp_ieee_div_zero 0
		.amdhsa_exception_fp_ieee_overflow 0
		.amdhsa_exception_fp_ieee_underflow 0
		.amdhsa_exception_fp_ieee_inexact 0
		.amdhsa_exception_int_div_zero 0
	.end_amdhsa_kernel

amdhsa.kernels:
  - .agpr_count:     0
    .args:
      - .offset:         0
        .size:           200
        .value_kind:     by_value
      - .offset:         200
        .size:           4
        .value_kind:     hidden_block_count_x
      - .offset:         204
        .size:           4
        .value_kind:     hidden_block_count_y
      - .offset:         208
        .size:           4
        .value_kind:     hidden_block_count_z
      - .offset:         212
        .size:           2
        .value_kind:     hidden_group_size_x
      - .offset:         214
        .size:           2
        .value_kind:     hidden_group_size_y
      - .offset:         216
        .size:           2
        .value_kind:     hidden_group_size_z
      - .offset:         218
        .size:           2
        .value_kind:     hidden_remainder_x
      - .offset:         220
        .size:           2
        .value_kind:     hidden_remainder_y
      - .offset:         222
        .size:           2
        .value_kind:     hidden_remainder_z
      - .offset:         240
        .size:           8
        .value_kind:     hidden_global_offset_x
      - .offset:         248
        .size:           8
        .value_kind:     hidden_global_offset_y
      - .offset:         256
        .size:           8
        .value_kind:     hidden_global_offset_z
      - .offset:         264
        .size:           2
        .value_kind:     hidden_grid_dims
      - .offset:         288
        .size:           8
        .value_kind:     hidden_multigrid_sync_arg
      - .offset:         320
        .size:           4
        .value_kind:     hidden_dynamic_lds_size
    .group_segment_fixed_size: 0
    .kernarg_segment_align: 8
    .kernarg_segment_size: 456
    .language:       OpenCL C
    .language_version:
      - 2
      - 0
    .max_flat_workgroup_size: 512
    .name:           _Z14fwd_megakernel6Params
    .private_segment_fixed_size: 0
    .sgpr_count:     108
    .sgpr_spill_count: 124
    .symbol:         _Z14fwd_megakernel6Params.kd
    .uniform_work_group_size: 1
    .uses_dynamic_stack: false
    .vgpr_count:     256
    .vgpr_spill_count: 0
    .wavefront_size: 64
